# FFN-down halo fix-up: six column iterations unrolled, all loads issued before one wait (de-serialised)
# speedup vs baseline: 1.0068x; 1.0043x over previous
; __device__ __forceinline__ int opaque_tid() { int t = threadIdx.x; asm volatile("" : "+v"(t)); return t; }
; #define INP(k) ((const float*)(const GASP float*)ldptr(PT, (k)))
; #define WSP(T, off) ((T*)(GASP T*)(ldptr(PT, 26) + (off)))
; __global__ void __launch_bounds__(NT, 2) trunk_fwd(Args args) {
;     ...
;             pg8::StaticOrder S; S.init(M, 1024, G, bx);
;             { const float* cw = INP(22) + (size_t)layer * 3 * 5632; const float* cb = INP(23) + (size_t)layer * 5632; const float* HALO = WSP(float, WS_HALO); bf16* GB = WSP(bf16, WS_G);
;             pg8::Unit u;
;             for (int i = 0; S.next(i, u); ++i) {
;                 const bool first = (u.pm % 32) == 0;
;                 for (int f = pg8::opaque_tid(); f < DFF; f += NT) { float cg0[2], cg1[2];
; #pragma unroll
;                     for (int part = 0; part < 2; ++part) { const int ch = part * DFF + f;
;                         const float um2 = first ? 0.f : HALO[(size_t)((u.pm - 1) * 4 + 2) * 5632 + ch], um1 = first ? 0.f : HALO[(size_t)((u.pm - 1) * 4 + 3) * 5632 + ch];
;                         const float u0 = HALO[(size_t)(u.pm * 4 + 0) * 5632 + ch], u1 = HALO[(size_t)(u.pm * 4 + 1) * 5632 + ch];
;                         const float w0 = cw[ch], w1 = cw[5632 + ch], w2 = cw[2 * 5632 + ch], bb = cb[ch];
;                         cg0[part] = bb + w0 * um2 + w1 * um1 + w2 * u0; cg1[part] = bb + w0 * um1 + w1 * u0 + w2 * u1; }
.LBB0_1269:
	v_mov_b32_e32 v2, v232
	s_nop 0
	v_cmp_gt_i32_e32 vcc, s37, v2
	s_and_saveexec_b64 s[12:13], vcc
	s_cbranch_execz .LBB0_1260
	s_and_b32 s0, s75, 31
	s_cmp_lg_u32 s0, 0
	s_cselect_b64 s[16:17], -1, 0
	s_lshl_b32 s0, s75, 2
	s_mul_i32 s1, s75, 0x16000
	s_mul_hi_i32 s21, s0, 0x5800
	s_add_u32 s20, s4, s1
	s_addc_u32 s21, s5, s21
	s_or_b32 s22, s0, 1
	s_mul_hi_i32 s23, s22, 0x5800
	s_mulk_i32 s22, 0x5800
	s_add_u32 s22, s4, s22
	s_addc_u32 s23, s5, s23
	s_add_i32 s24, s0, -1
	s_add_i32 s25, s1, 0xffffa800
	s_mul_hi_i32 s26, s24, 0x5800
	s_add_u32 s24, s4, s25
	s_addc_u32 s25, s5, s26
	s_lshl_b32 s33, s75, 8
	s_mul_i32 s26, s75, 0x160000
	s_mul_hi_i32 s27, s33, 0x1600
	s_add_u32 s26, s14, s26
	s_addc_u32 s27, s15, s27
	s_or_b32 s33, s33, 1
	s_mul_hi_i32 s36, s33, 0x1600
	s_mulk_i32 s33, 0x1600
	s_add_u32 s38, s14, s33
	s_addc_u32 s39, s15, s36
	s_add_i32 s0, s0, -4
	s_add_i32 s1, s1, 0xfffea000
	s_mul_hi_i32 s33, s0, 0x5800
	s_add_u32 s0, s28, s1
	v_add_u32_e32 v6, 0xb00, v2
	v_ashrrev_i32_e32 v3, 31, v2
	s_addc_u32 s1, s30, s33
	v_ashrrev_i32_e32 v7, 31, v6
	v_lshl_add_u64 v[4:5], v[2:3], 2, s[0:1]
	v_lshl_add_u64 v[8:9], v[6:7], 2, s[0:1]
	v_mov_b32_e32 v15, 0
	s_and_b64 vcc, exec, s[16:17]
	v_mov_b64_e32 v[10:11], v[2:3]
	v_mov_b32_e32 v17, 0
	s_cbranch_vccz .Lhalo0_1274
	global_load_dword v17, v[4:5], off
	v_ashrrev_i32_e32 v11, 31, v2
	v_mov_b32_e32 v10, v2

; __device__ __forceinline__ int opaque_tid() { int t = threadIdx.x; asm volatile("" : "+v"(t)); return t; }
; __global__ void __launch_bounds__(NT, 2) trunk_fwd(Args args) {
;     ...
;                 for (int f = pg8::opaque_tid(); f < DFF; f += NT) { float cg0[2], cg1[2];
; #pragma unroll
;                     for (int part = 0; part < 2; ++part) { const int ch = part * DFF + f;
;                         const float um2 = first ? 0.f : HALO[(size_t)((u.pm - 1) * 4 + 2) * 5632 + ch], um1 = first ? 0.f : HALO[(size_t)((u.pm - 1) * 4 + 3) * 5632 + ch];
;                         const float u0 = HALO[(size_t)(u.pm * 4 + 0) * 5632 + ch], u1 = HALO[(size_t)(u.pm * 4 + 1) * 5632 + ch];
;                         const float w0 = cw[ch], w1 = cw[5632 + ch], w2 = cw[2 * 5632 + ch], bb = cb[ch];
;                         cg0[part] = bb + w0 * um2 + w1 * um1 + w2 * u0; cg1[part] = bb + w0 * um1 + w1 * u0 + w2 * u1; }
.Lhalo0_b:
	v_lshlrev_b64 v[12:13], 2, v[12:13]
	v_lshl_add_u64 v[26:27], s[20:21], 0, v[12:13]
	global_load_dword v38, v[26:27], off
	v_lshl_add_u64 v[26:27], s[22:23], 0, v[12:13]
	global_load_dword v39, v[26:27], off
	v_lshl_add_u64 v[26:27], s[6:7], 0, v[12:13]
	v_add_co_u32_e32 v28, vcc, 0x5000, v26
	v_lshl_add_u64 v[12:13], s[10:11], 0, v[12:13]
	global_load_dword v40, v[26:27], off
	v_addc_co_u32_e32 v29, vcc, 0, v27, vcc
	global_load_dword v41, v[12:13], off
	v_lshlrev_b64 v[10:11], 1, v[10:11]
	global_load_dword v42, v[28:29], off offset:2048
	v_add_co_u32_e32 v26, vcc, 0xb000, v26
	v_lshl_add_u64 v[2:3], v[2:3], 0, s[96:97]
	s_nop 0
	v_addc_co_u32_e32 v27, vcc, 0, v27, vcc
	global_load_dword v43, v[26:27], off
	v_lshl_add_u64 v[4:5], v[4:5], 0, s[84:85]
	v_lshl_add_u64 v[6:7], v[6:7], 0, s[96:97]
	v_lshl_add_u64 v[8:9], v[8:9], 0, s[84:85]
	v_mov_b32_e32 v69, 0
	s_and_b64 vcc, exec, s[16:17]
	v_mov_b64_e32 v[64:65], v[2:3]
	v_mov_b32_e32 v71, 0
	s_cbranch_vccz .Lhalo1_1274
	global_load_dword v71, v[4:5], off
	v_ashrrev_i32_e32 v65, 31, v2
	v_mov_b32_e32 v64, v2
.Lhalo1_1274:
	v_cndmask_b32_e64 v214, 0, 1, s[16:17]
	v_cmp_ne_u32_e64 s[0:1], 1, v214
	s_andn2_b64 vcc, exec, s[16:17]
	s_cbranch_vccnz .Lhalo1_1276
	v_lshl_add_u64 v[66:67], v[64:65], 2, s[24:25]
	global_load_dword v69, v[66:67], off
.Lhalo1_1276:
	v_lshlrev_b64 v[66:67], 2, v[64:65]
	v_lshl_add_u64 v[76:77], s[6:7], 0, v[66:67]
	v_add_co_u32_e32 v78, vcc, 0x5000, v76
	v_lshl_add_u64 v[72:73], s[20:21], 0, v[66:67]
	v_lshl_add_u64 v[74:75], s[22:23], 0, v[66:67]
	v_addc_co_u32_e32 v79, vcc, 0, v77, vcc
	global_load_dword v72, v[72:73], off
	v_lshl_add_u64 v[66:67], s[10:11], 0, v[66:67]
	global_load_dword v73, v[74:75], off
	global_load_dword v214, v[66:67], off
	v_mov_b32_e32 v68, 0
	global_load_dword v74, v[76:77], off
	global_load_dword v75, v[78:79], off offset:2048
	v_add_co_u32_e32 v76, vcc, 0xb000, v76
	v_mov_b64_e32 v[66:67], v[6:7]
	s_nop 0
	v_addc_co_u32_e32 v77, vcc, 0, v77, vcc
	global_load_dword v76, v[76:77], off
	s_and_b64 vcc, exec, s[0:1]
	v_mov_b32_e32 v70, 0
	s_cbranch_vccnz .Lhalo1_1278
	global_load_dword v70, v[8:9], off
	v_add_u32_e32 v66, 0xb00, v2
	v_ashrrev_i32_e32 v67, 31, v66
.Lhalo1_1278:
	s_and_b64 vcc, exec, s[0:1]
	s_cbranch_vccnz .Lhalo1_b
	v_lshl_add_u64 v[78:79], v[66:67], 2, s[24:25]
	global_load_dword v68, v[78:79], off
	s_branch .Lhalo1_b
.Lhalo1_b:
	v_lshlrev_b64 v[66:67], 2, v[66:67]
	v_lshl_add_u64 v[26:27], s[20:21], 0, v[66:67]
	global_load_dword v182, v[26:27], off
	v_lshl_add_u64 v[26:27], s[22:23], 0, v[66:67]
	global_load_dword v183, v[26:27], off
	v_lshl_add_u64 v[26:27], s[6:7], 0, v[66:67]
	v_add_co_u32_e32 v28, vcc, 0x5000, v26
	v_lshl_add_u64 v[66:67], s[10:11], 0, v[66:67]
	global_load_dword v184, v[26:27], off
	v_addc_co_u32_e32 v29, vcc, 0, v27, vcc
	global_load_dword v185, v[66:67], off
	v_lshlrev_b64 v[64:65], 1, v[64:65]
	global_load_dword v186, v[28:29], off offset:2048
	v_add_co_u32_e32 v26, vcc, 0xb000, v26
	v_lshl_add_u64 v[2:3], v[2:3], 0, s[96:97]
	s_nop 0
	v_addc_co_u32_e32 v27, vcc, 0, v27, vcc
	global_load_dword v187, v[26:27], off
	v_lshl_add_u64 v[4:5], v[4:5], 0, s[84:85]
	v_lshl_add_u64 v[6:7], v[6:7], 0, s[96:97]
	v_lshl_add_u64 v[8:9], v[8:9], 0, s[84:85]
	v_mov_b32_e32 v103, 0
	s_and_b64 vcc, exec, s[16:17]
	v_mov_b64_e32 v[98:99], v[2:3]
	v_mov_b32_e32 v105, 0
	s_cbranch_vccz .Lhalo2_1274
	global_load_dword v105, v[4:5], off
	v_ashrrev_i32_e32 v99, 31, v2
	v_mov_b32_e32 v98, v2
.Lhalo2_1274:
	v_cndmask_b32_e64 v215, 0, 1, s[16:17]
	v_cmp_ne_u32_e64 s[0:1], 1, v215
	s_andn2_b64 vcc, exec, s[16:17]
	s_cbranch_vccnz .Lhalo2_1276
	v_lshl_add_u64 v[100:101], v[98:99], 2, s[24:25]
	global_load_dword v103, v[100:101], off
.Lhalo2_1276:
	v_lshlrev_b64 v[100:101], 2, v[98:99]
	v_lshl_add_u64 v[110:111], s[6:7], 0, v[100:101]
	v_add_co_u32_e32 v112, vcc, 0x5000, v110
	v_lshl_add_u64 v[106:107], s[20:21], 0, v[100:101]
	v_lshl_add_u64 v[108:109], s[22:23], 0, v[100:101]
	v_addc_co_u32_e32 v113, vcc, 0, v111, vcc
	global_load_dword v106, v[106:107], off
	v_lshl_add_u64 v[100:101], s[10:11], 0, v[100:101]
	global_load_dword v107, v[108:109], off
	global_load_dword v215, v[100:101], off
	v_mov_b32_e32 v102, 0
	global_load_dword v108, v[110:111], off
	global_load_dword v109, v[112:113], off offset:2048
	v_add_co_u32_e32 v110, vcc, 0xb000, v110
	v_mov_b64_e32 v[100:101], v[6:7]
	s_nop 0
	v_addc_co_u32_e32 v111, vcc, 0, v111, vcc
	global_load_dword v110, v[110:111], off
	s_and_b64 vcc, exec, s[0:1]
	v_mov_b32_e32 v104, 0
	s_cbranch_vccnz .Lhalo2_1278
	global_load_dword v104, v[8:9], off
	v_add_u32_e32 v100, 0xb00, v2
	v_ashrrev_i32_e32 v101, 31, v100
.Lhalo2_1278:
	s_and_b64 vcc, exec, s[0:1]
	s_cbranch_vccnz .Lhalo2_b
	v_lshl_add_u64 v[112:113], v[100:101], 2, s[24:25]
	global_load_dword v102, v[112:113], off
	s_branch .Lhalo2_b
.Lhalo2_b:
	v_lshlrev_b64 v[100:101], 2, v[100:101]
	v_lshl_add_u64 v[26:27], s[20:21], 0, v[100:101]
	global_load_dword v188, v[26:27], off
	v_lshl_add_u64 v[26:27], s[22:23], 0, v[100:101]
	global_load_dword v189, v[26:27], off
	v_lshl_add_u64 v[26:27], s[6:7], 0, v[100:101]
	v_add_co_u32_e32 v28, vcc, 0x5000, v26
	v_lshl_add_u64 v[100:101], s[10:11], 0, v[100:101]
	global_load_dword v190, v[26:27], off
	v_addc_co_u32_e32 v29, vcc, 0, v27, vcc
	global_load_dword v191, v[100:101], off
	v_lshlrev_b64 v[98:99], 1, v[98:99]
	global_load_dword v192, v[28:29], off offset:2048
	v_add_co_u32_e32 v26, vcc, 0xb000, v26
	v_lshl_add_u64 v[2:3], v[2:3], 0, s[96:97]
	s_nop 0
	v_addc_co_u32_e32 v27, vcc, 0, v27, vcc
	global_load_dword v193, v[26:27], off
	v_lshl_add_u64 v[4:5], v[4:5], 0, s[84:85]
	v_lshl_add_u64 v[6:7], v[6:7], 0, s[96:97]
	v_lshl_add_u64 v[8:9], v[8:9], 0, s[84:85]
	v_mov_b32_e32 v119, 0
	s_and_b64 vcc, exec, s[16:17]
	v_mov_b64_e32 v[114:115], v[2:3]
	v_mov_b32_e32 v121, 0
	s_cbranch_vccz .Lhalo3_1274
	global_load_dword v121, v[4:5], off
	v_ashrrev_i32_e32 v115, 31, v2
	v_mov_b32_e32 v114, v2
; __device__ __forceinline__ int opaque_tid() { int t = threadIdx.x; asm volatile("" : "+v"(t)); return t; }
; __global__ void __launch_bounds__(NT, 2) trunk_fwd(Args args) {
;     ...
;                 for (int f = pg8::opaque_tid(); f < DFF; f += NT) { float cg0[2], cg1[2];
; #pragma unroll
;                     for (int part = 0; part < 2; ++part) { const int ch = part * DFF + f;
;                         const float um2 = first ? 0.f : HALO[(size_t)((u.pm - 1) * 4 + 2) * 5632 + ch], um1 = first ? 0.f : HALO[(size_t)((u.pm - 1) * 4 + 3) * 5632 + ch];
;                         const float u0 = HALO[(size_t)(u.pm * 4 + 0) * 5632 + ch], u1 = HALO[(size_t)(u.pm * 4 + 1) * 5632 + ch];
;                         const float w0 = cw[ch], w1 = cw[5632 + ch], w2 = cw[2 * 5632 + ch], bb = cb[ch];
;                         cg0[part] = bb + w0 * um2 + w1 * um1 + w2 * u0; cg1[part] = bb + w0 * um1 + w1 * u0 + w2 * u1; }
.Lhalo3_1274:
	v_cndmask_b32_e64 v216, 0, 1, s[16:17]
	v_cmp_ne_u32_e64 s[0:1], 1, v216
	s_andn2_b64 vcc, exec, s[16:17]
	s_cbranch_vccnz .Lhalo3_1276
	v_lshl_add_u64 v[116:117], v[114:115], 2, s[24:25]
	global_load_dword v119, v[116:117], off
.Lhalo3_1276:
	v_lshlrev_b64 v[116:117], 2, v[114:115]
	v_lshl_add_u64 v[126:127], s[6:7], 0, v[116:117]
	v_add_co_u32_e32 v128, vcc, 0x5000, v126
	v_lshl_add_u64 v[122:123], s[20:21], 0, v[116:117]
	v_lshl_add_u64 v[124:125], s[22:23], 0, v[116:117]
	v_addc_co_u32_e32 v129, vcc, 0, v127, vcc
	global_load_dword v122, v[122:123], off
	v_lshl_add_u64 v[116:117], s[10:11], 0, v[116:117]
	global_load_dword v123, v[124:125], off
	global_load_dword v216, v[116:117], off
	v_mov_b32_e32 v118, 0
	global_load_dword v124, v[126:127], off
	global_load_dword v125, v[128:129], off offset:2048
	v_add_co_u32_e32 v126, vcc, 0xb000, v126
	v_mov_b64_e32 v[116:117], v[6:7]
	s_nop 0
	v_addc_co_u32_e32 v127, vcc, 0, v127, vcc
	global_load_dword v126, v[126:127], off
	s_and_b64 vcc, exec, s[0:1]
	v_mov_b32_e32 v120, 0
	s_cbranch_vccnz .Lhalo3_1278
	global_load_dword v120, v[8:9], off
	v_add_u32_e32 v116, 0xb00, v2
	v_ashrrev_i32_e32 v117, 31, v116
.Lhalo3_1278:
	s_and_b64 vcc, exec, s[0:1]
	s_cbranch_vccnz .Lhalo3_b
	v_lshl_add_u64 v[128:129], v[116:117], 2, s[24:25]
	global_load_dword v118, v[128:129], off
	s_branch .Lhalo3_b
.Lhalo3_b:
	v_lshlrev_b64 v[116:117], 2, v[116:117]
	v_lshl_add_u64 v[26:27], s[20:21], 0, v[116:117]
	global_load_dword v196, v[26:27], off
	v_lshl_add_u64 v[26:27], s[22:23], 0, v[116:117]
	global_load_dword v197, v[26:27], off
	v_lshl_add_u64 v[26:27], s[6:7], 0, v[116:117]
	v_add_co_u32_e32 v28, vcc, 0x5000, v26
	v_lshl_add_u64 v[116:117], s[10:11], 0, v[116:117]
	global_load_dword v198, v[26:27], off
	v_addc_co_u32_e32 v29, vcc, 0, v27, vcc
	global_load_dword v199, v[116:117], off
	v_lshlrev_b64 v[114:115], 1, v[114:115]
	global_load_dword v200, v[28:29], off offset:2048
	v_add_co_u32_e32 v26, vcc, 0xb000, v26
	v_lshl_add_u64 v[2:3], v[2:3], 0, s[96:97]
	s_nop 0
	v_addc_co_u32_e32 v27, vcc, 0, v27, vcc
	global_load_dword v201, v[26:27], off
	v_lshl_add_u64 v[4:5], v[4:5], 0, s[84:85]
	v_lshl_add_u64 v[6:7], v[6:7], 0, s[96:97]
	v_lshl_add_u64 v[8:9], v[8:9], 0, s[84:85]
	v_mov_b32_e32 v135, 0
	s_and_b64 vcc, exec, s[16:17]
	v_mov_b64_e32 v[130:131], v[2:3]
	v_mov_b32_e32 v137, 0
	s_cbranch_vccz .Lhalo4_1274
	global_load_dword v137, v[4:5], off
	v_ashrrev_i32_e32 v131, 31, v2
	v_mov_b32_e32 v130, v2
.Lhalo4_1274:
	v_cndmask_b32_e64 v217, 0, 1, s[16:17]
	v_cmp_ne_u32_e64 s[0:1], 1, v217
	s_andn2_b64 vcc, exec, s[16:17]
	s_cbranch_vccnz .Lhalo4_1276
	v_lshl_add_u64 v[132:133], v[130:131], 2, s[24:25]
	global_load_dword v135, v[132:133], off
.Lhalo4_1276:
	v_lshlrev_b64 v[132:133], 2, v[130:131]
	v_lshl_add_u64 v[142:143], s[6:7], 0, v[132:133]
	v_add_co_u32_e32 v144, vcc, 0x5000, v142
	v_lshl_add_u64 v[138:139], s[20:21], 0, v[132:133]
	v_lshl_add_u64 v[140:141], s[22:23], 0, v[132:133]
	v_addc_co_u32_e32 v145, vcc, 0, v143, vcc
	global_load_dword v138, v[138:139], off
	v_lshl_add_u64 v[132:133], s[10:11], 0, v[132:133]
	global_load_dword v139, v[140:141], off
	global_load_dword v217, v[132:133], off
	v_mov_b32_e32 v134, 0
	global_load_dword v140, v[142:143], off
	global_load_dword v141, v[144:145], off offset:2048
	v_add_co_u32_e32 v142, vcc, 0xb000, v142
	v_mov_b64_e32 v[132:133], v[6:7]
	s_nop 0
	v_addc_co_u32_e32 v143, vcc, 0, v143, vcc
	global_load_dword v142, v[142:143], off
	s_and_b64 vcc, exec, s[0:1]
	v_mov_b32_e32 v136, 0
	s_cbranch_vccnz .Lhalo4_1278
	global_load_dword v136, v[8:9], off
	v_add_u32_e32 v132, 0xb00, v2
	v_ashrrev_i32_e32 v133, 31, v132
.Lhalo4_1278:
	s_and_b64 vcc, exec, s[0:1]
	s_cbranch_vccnz .Lhalo4_b
	v_lshl_add_u64 v[144:145], v[132:133], 2, s[24:25]
	global_load_dword v134, v[144:145], off
	s_branch .Lhalo4_b
.Lhalo4_b:
	v_lshlrev_b64 v[132:133], 2, v[132:133]
	v_lshl_add_u64 v[26:27], s[20:21], 0, v[132:133]
	global_load_dword v202, v[26:27], off
	v_lshl_add_u64 v[26:27], s[22:23], 0, v[132:133]
	global_load_dword v203, v[26:27], off
	v_lshl_add_u64 v[26:27], s[6:7], 0, v[132:133]
	v_add_co_u32_e32 v28, vcc, 0x5000, v26
	v_lshl_add_u64 v[132:133], s[10:11], 0, v[132:133]
	global_load_dword v204, v[26:27], off
	v_addc_co_u32_e32 v29, vcc, 0, v27, vcc
	global_load_dword v205, v[132:133], off
	v_lshlrev_b64 v[130:131], 1, v[130:131]
	global_load_dword v206, v[28:29], off offset:2048
	v_add_co_u32_e32 v26, vcc, 0xb000, v26
	v_lshl_add_u64 v[2:3], v[2:3], 0, s[96:97]
	s_nop 0
	v_addc_co_u32_e32 v27, vcc, 0, v27, vcc
	global_load_dword v207, v[26:27], off
	v_lshl_add_u64 v[4:5], v[4:5], 0, s[84:85]
	v_lshl_add_u64 v[6:7], v[6:7], 0, s[96:97]
	v_lshl_add_u64 v[8:9], v[8:9], 0, s[84:85]
	v_cmp_gt_i32_e32 vcc, s37, v2
	s_mov_b64 s[44:45], vcc
	s_and_saveexec_b64 s[40:41], vcc
	v_mov_b32_e32 v151, 0
	s_and_b64 vcc, exec, s[16:17]
	v_mov_b64_e32 v[146:147], v[2:3]
	v_mov_b32_e32 v153, 0
	s_cbranch_vccz .Lhalo5_1274
	global_load_dword v153, v[4:5], off
	v_ashrrev_i32_e32 v147, 31, v2
	v_mov_b32_e32 v146, v2
.Lhalo5_1274:
	v_cndmask_b32_e64 v218, 0, 1, s[16:17]
	v_cmp_ne_u32_e64 s[0:1], 1, v218
	s_andn2_b64 vcc, exec, s[16:17]
	s_cbranch_vccnz .Lhalo5_1276
	v_lshl_add_u64 v[148:149], v[146:147], 2, s[24:25]
	global_load_dword v151, v[148:149], off
; __device__ __forceinline__ int opaque_tid() { int t = threadIdx.x; asm volatile("" : "+v"(t)); return t; }
; __device__ __forceinline__ unsigned pk2(float lo, float hi) { f32x2_t v = {lo, hi}; bf16x2_t b = __builtin_convertvector(v, bf16x2_t); return __builtin_bit_cast(unsigned, b); }
; __global__ void __launch_bounds__(NT, 2) trunk_fwd(Args args) {
;     ...
;                 for (int f = pg8::opaque_tid(); f < DFF; f += NT) { float cg0[2], cg1[2];
; #pragma unroll
;                     for (int part = 0; part < 2; ++part) { const int ch = part * DFF + f;
;                         const float um2 = first ? 0.f : HALO[(size_t)((u.pm - 1) * 4 + 2) * 5632 + ch], um1 = first ? 0.f : HALO[(size_t)((u.pm - 1) * 4 + 3) * 5632 + ch];
;                         const float u0 = HALO[(size_t)(u.pm * 4 + 0) * 5632 + ch], u1 = HALO[(size_t)(u.pm * 4 + 1) * 5632 + ch];
;                         const float w0 = cw[ch], w1 = cw[5632 + ch], w2 = cw[2 * 5632 + ch], bb = cb[ch];
;                         cg0[part] = bb + w0 * um2 + w1 * um1 + w2 * u0; cg1[part] = bb + w0 * um1 + w1 * u0 + w2 * u1; }
;                     const float g0 = cg0[0] / (1.0f + __expf(-cg0[0])) * cg0[1], g1 = cg1[0] / (1.0f + __expf(-cg1[0])) * cg1[1];
;                     GB[(size_t)(u.pm * 256) * DFF + f] = (bf16)(pk2(g0, 0.f) & 0xffffu); GB[(size_t)(u.pm * 256 + 1) * DFF + f] = (bf16)(pk2(g1, 0.f) & 0xffffu); }
.Lhalo5_1276:
	v_lshlrev_b64 v[148:149], 2, v[146:147]
	v_lshl_add_u64 v[158:159], s[6:7], 0, v[148:149]
	v_add_co_u32_e32 v160, vcc, 0x5000, v158
	v_lshl_add_u64 v[154:155], s[20:21], 0, v[148:149]
	v_lshl_add_u64 v[156:157], s[22:23], 0, v[148:149]
	v_addc_co_u32_e32 v161, vcc, 0, v159, vcc
	global_load_dword v154, v[154:155], off
	v_lshl_add_u64 v[148:149], s[10:11], 0, v[148:149]
	global_load_dword v155, v[156:157], off
	global_load_dword v218, v[148:149], off
	v_mov_b32_e32 v150, 0
	global_load_dword v156, v[158:159], off
	global_load_dword v157, v[160:161], off offset:2048
	v_add_co_u32_e32 v158, vcc, 0xb000, v158
	v_mov_b64_e32 v[148:149], v[6:7]
	s_nop 0
	v_addc_co_u32_e32 v159, vcc, 0, v159, vcc
	global_load_dword v158, v[158:159], off
	s_and_b64 vcc, exec, s[0:1]
	v_mov_b32_e32 v152, 0
	s_cbranch_vccnz .Lhalo5_1278
	global_load_dword v152, v[8:9], off
	v_add_u32_e32 v148, 0xb00, v2
	v_ashrrev_i32_e32 v149, 31, v148
.Lhalo5_1278:
	s_and_b64 vcc, exec, s[0:1]
	s_cbranch_vccnz .Lhalo5_b
	v_lshl_add_u64 v[160:161], v[148:149], 2, s[24:25]
	global_load_dword v150, v[160:161], off
	s_branch .Lhalo5_b
.Lhalo5_b:
	v_lshlrev_b64 v[148:149], 2, v[148:149]
	v_lshl_add_u64 v[26:27], s[20:21], 0, v[148:149]
	global_load_dword v208, v[26:27], off
	v_lshl_add_u64 v[26:27], s[22:23], 0, v[148:149]
	global_load_dword v209, v[26:27], off
	v_lshl_add_u64 v[26:27], s[6:7], 0, v[148:149]
	v_add_co_u32_e32 v28, vcc, 0x5000, v26
	v_lshl_add_u64 v[148:149], s[10:11], 0, v[148:149]
	global_load_dword v210, v[26:27], off
	v_addc_co_u32_e32 v29, vcc, 0, v27, vcc
	global_load_dword v211, v[148:149], off
	v_lshlrev_b64 v[146:147], 1, v[146:147]
	global_load_dword v212, v[28:29], off offset:2048
	v_add_co_u32_e32 v26, vcc, 0xb000, v26
	v_lshl_add_u64 v[2:3], v[2:3], 0, s[96:97]
	s_nop 0
	v_addc_co_u32_e32 v27, vcc, 0, v27, vcc
	global_load_dword v213, v[26:27], off
	v_lshl_add_u64 v[4:5], v[4:5], 0, s[84:85]
	v_lshl_add_u64 v[6:7], v[6:7], 0, s[96:97]
	v_lshl_add_u64 v[8:9], v[8:9], 0, s[84:85]
	s_or_b64 exec, exec, s[40:41]
	s_waitcnt vmcnt(0)
	v_fma_f32 v17, v17, v20, v0
	v_fmac_f32_e32 v0, v15, v20
	v_fmac_f32_e32 v17, v15, v21
	v_fmac_f32_e32 v0, v18, v21
	v_fmac_f32_e32 v17, v18, v22
	v_fmac_f32_e32 v0, v19, v22
	v_fma_f32 v13, v16, v40, v41
	v_fmac_f32_e32 v41, v14, v40
	v_fmac_f32_e32 v13, v14, v42
	v_mul_f32_e32 v14, 0xbfb8aa3b, v17
	v_exp_f32_e32 v14, v14
	v_fmac_f32_e32 v41, v38, v42
	v_add_f32_e32 v14, 1.0, v14
	v_fmac_f32_e32 v13, v38, v43
	v_div_scale_f32 v15, s[0:1], v14, v14, v17
	v_rcp_f32_e32 v16, v15
	v_fmac_f32_e32 v41, v39, v43
	v_fma_f32 v18, -v15, v16, 1.0
	v_fmac_f32_e32 v16, v18, v16
	v_div_scale_f32 v18, vcc, v17, v14, v17
	v_mul_f32_e32 v19, v18, v16
	v_fma_f32 v20, -v15, v19, v18
	v_fmac_f32_e32 v19, v20, v16
	v_fma_f32 v15, -v15, v19, v18
	v_div_fmas_f32 v15, v15, v16, v19
	v_div_fixup_f32 v14, v15, v14, v17
	v_mul_f32_e32 v13, v13, v14
	v_mul_f32_e32 v14, 0xbfb8aa3b, v0
	v_exp_f32_e32 v14, v14
	s_nop 0
	v_add_f32_e32 v14, 1.0, v14
	v_div_scale_f32 v15, s[0:1], v14, v14, v0
	v_rcp_f32_e32 v16, v15
	s_nop 0
	v_fma_f32 v17, -v15, v16, 1.0
	v_fmac_f32_e32 v16, v17, v16
	v_div_scale_f32 v17, vcc, v0, v14, v0
	v_mul_f32_e32 v18, v17, v16
	v_fma_f32 v19, -v15, v18, v17
	v_fmac_f32_e32 v18, v19, v16
	v_fma_f32 v15, -v15, v18, v17
	v_div_fmas_f32 v15, v15, v16, v18
	v_div_fixup_f32 v0, v15, v14, v0
	v_mul_f32_e32 v0, v41, v0
	v_cvt_pk_bf16_f32 v14, v13, s0
	v_lshl_add_u64 v[12:13], s[26:27], 0, v[10:11]
	v_cvt_pk_bf16_f32 v0, v0, s0
	v_lshl_add_u64 v[10:11], s[38:39], 0, v[10:11]
	global_store_short v[10:11], v0, off
	global_store_short v[12:13], v14, off
	v_fma_f32 v71, v71, v74, v214
	v_fmac_f32_e32 v214, v69, v74
	v_fmac_f32_e32 v71, v69, v75
	v_fmac_f32_e32 v214, v72, v75
	v_fmac_f32_e32 v71, v72, v76
	v_fmac_f32_e32 v214, v73, v76
	v_fma_f32 v67, v70, v184, v185
	v_fmac_f32_e32 v185, v68, v184
	v_fmac_f32_e32 v67, v68, v186
	v_mul_f32_e32 v68, 0xbfb8aa3b, v71
	v_exp_f32_e32 v68, v68
	v_fmac_f32_e32 v185, v182, v186
	v_add_f32_e32 v68, 1.0, v68
	v_fmac_f32_e32 v67, v182, v187
	v_div_scale_f32 v69, s[0:1], v68, v68, v71
	v_rcp_f32_e32 v70, v69
	v_fmac_f32_e32 v185, v183, v187
	v_fma_f32 v72, -v69, v70, 1.0
	v_fmac_f32_e32 v70, v72, v70
	v_div_scale_f32 v72, vcc, v71, v68, v71
	v_mul_f32_e32 v73, v72, v70
	v_fma_f32 v74, -v69, v73, v72
	v_fmac_f32_e32 v73, v74, v70
	v_fma_f32 v69, -v69, v73, v72
	v_div_fmas_f32 v69, v69, v70, v73
	v_div_fixup_f32 v68, v69, v68, v71
	v_mul_f32_e32 v67, v67, v68
	v_mul_f32_e32 v68, 0xbfb8aa3b, v214
	v_exp_f32_e32 v68, v68
	s_nop 0
	v_add_f32_e32 v68, 1.0, v68
	v_div_scale_f32 v69, s[0:1], v68, v68, v214
	v_rcp_f32_e32 v70, v69
	s_nop 0
	v_fma_f32 v71, -v69, v70, 1.0
	v_fmac_f32_e32 v70, v71, v70
	v_div_scale_f32 v71, vcc, v214, v68, v214
	v_mul_f32_e32 v72, v71, v70
	v_fma_f32 v73, -v69, v72, v71
	v_fmac_f32_e32 v72, v73, v70
	v_fma_f32 v69, -v69, v72, v71
	v_div_fmas_f32 v69, v69, v70, v72
	v_div_fixup_f32 v214, v69, v68, v214
	v_mul_f32_e32 v214, v185, v214
	v_cvt_pk_bf16_f32 v68, v67, s0
	v_lshl_add_u64 v[66:67], s[26:27], 0, v[64:65]
	v_cvt_pk_bf16_f32 v214, v214, s0
	v_lshl_add_u64 v[64:65], s[38:39], 0, v[64:65]
	global_store_short v[64:65], v214, off
	global_store_short v[66:67], v68, off
	v_fma_f32 v105, v105, v108, v215
	v_fmac_f32_e32 v215, v103, v108
	v_fmac_f32_e32 v105, v103, v109
	v_fmac_f32_e32 v215, v106, v109
	v_fmac_f32_e32 v105, v106, v110
	v_fmac_f32_e32 v215, v107, v110
	v_fma_f32 v101, v104, v190, v191
	v_fmac_f32_e32 v191, v102, v190
	v_fmac_f32_e32 v101, v102, v192
	v_mul_f32_e32 v102, 0xbfb8aa3b, v105
	v_exp_f32_e32 v102, v102
	v_fmac_f32_e32 v191, v188, v192
	v_add_f32_e32 v102, 1.0, v102
; __device__ __forceinline__ int opaque_tid() { int t = threadIdx.x; asm volatile("" : "+v"(t)); return t; }
; __device__ __forceinline__ unsigned pk2(float lo, float hi) { f32x2_t v = {lo, hi}; bf16x2_t b = __builtin_convertvector(v, bf16x2_t); return __builtin_bit_cast(unsigned, b); }
; __global__ void __launch_bounds__(NT, 2) trunk_fwd(Args args) {
;     ...
;                 for (int f = pg8::opaque_tid(); f < DFF; f += NT) { float cg0[2], cg1[2];
; #pragma unroll
;                     for (int part = 0; part < 2; ++part) { const int ch = part * DFF + f;
;                         const float um2 = first ? 0.f : HALO[(size_t)((u.pm - 1) * 4 + 2) * 5632 + ch], um1 = first ? 0.f : HALO[(size_t)((u.pm - 1) * 4 + 3) * 5632 + ch];
;                         const float u0 = HALO[(size_t)(u.pm * 4 + 0) * 5632 + ch], u1 = HALO[(size_t)(u.pm * 4 + 1) * 5632 + ch];
;                         const float w0 = cw[ch], w1 = cw[5632 + ch], w2 = cw[2 * 5632 + ch], bb = cb[ch];
;                         cg0[part] = bb + w0 * um2 + w1 * um1 + w2 * u0; cg1[part] = bb + w0 * um1 + w1 * u0 + w2 * u1; }
;                     const float g0 = cg0[0] / (1.0f + __expf(-cg0[0])) * cg0[1], g1 = cg1[0] / (1.0f + __expf(-cg1[0])) * cg1[1];
;                     GB[(size_t)(u.pm * 256) * DFF + f] = (bf16)(pk2(g0, 0.f) & 0xffffu); GB[(size_t)(u.pm * 256 + 1) * DFF + f] = (bf16)(pk2(g1, 0.f) & 0xffffu); }
	v_fmac_f32_e32 v101, v188, v193
	v_div_scale_f32 v103, s[0:1], v102, v102, v105
	v_rcp_f32_e32 v104, v103
	v_fmac_f32_e32 v191, v189, v193
	v_fma_f32 v106, -v103, v104, 1.0
	v_fmac_f32_e32 v104, v106, v104
	v_div_scale_f32 v106, vcc, v105, v102, v105
	v_mul_f32_e32 v107, v106, v104
	v_fma_f32 v108, -v103, v107, v106
	v_fmac_f32_e32 v107, v108, v104
	v_fma_f32 v103, -v103, v107, v106
	v_div_fmas_f32 v103, v103, v104, v107
	v_div_fixup_f32 v102, v103, v102, v105
	v_mul_f32_e32 v101, v101, v102
	v_mul_f32_e32 v102, 0xbfb8aa3b, v215
	v_exp_f32_e32 v102, v102
	s_nop 0
	v_add_f32_e32 v102, 1.0, v102
	v_div_scale_f32 v103, s[0:1], v102, v102, v215
	v_rcp_f32_e32 v104, v103
	s_nop 0
	v_fma_f32 v105, -v103, v104, 1.0
	v_fmac_f32_e32 v104, v105, v104
	v_div_scale_f32 v105, vcc, v215, v102, v215
	v_mul_f32_e32 v106, v105, v104
	v_fma_f32 v107, -v103, v106, v105
	v_fmac_f32_e32 v106, v107, v104
	v_fma_f32 v103, -v103, v106, v105
	v_div_fmas_f32 v103, v103, v104, v106
	v_div_fixup_f32 v215, v103, v102, v215
	v_mul_f32_e32 v215, v191, v215
	v_cvt_pk_bf16_f32 v102, v101, s0
	v_lshl_add_u64 v[100:101], s[26:27], 0, v[98:99]
	v_cvt_pk_bf16_f32 v215, v215, s0
	v_lshl_add_u64 v[98:99], s[38:39], 0, v[98:99]
	global_store_short v[98:99], v215, off
	global_store_short v[100:101], v102, off
	v_fma_f32 v121, v121, v124, v216
	v_fmac_f32_e32 v216, v119, v124
	v_fmac_f32_e32 v121, v119, v125
	v_fmac_f32_e32 v216, v122, v125
	v_fmac_f32_e32 v121, v122, v126
	v_fmac_f32_e32 v216, v123, v126
	v_fma_f32 v117, v120, v198, v199
	v_fmac_f32_e32 v199, v118, v198
	v_fmac_f32_e32 v117, v118, v200
	v_mul_f32_e32 v118, 0xbfb8aa3b, v121
	v_exp_f32_e32 v118, v118
	v_fmac_f32_e32 v199, v196, v200
	v_add_f32_e32 v118, 1.0, v118
	v_fmac_f32_e32 v117, v196, v201
	v_div_scale_f32 v119, s[0:1], v118, v118, v121
	v_rcp_f32_e32 v120, v119
	v_fmac_f32_e32 v199, v197, v201
	v_fma_f32 v122, -v119, v120, 1.0
	v_fmac_f32_e32 v120, v122, v120
	v_div_scale_f32 v122, vcc, v121, v118, v121
	v_mul_f32_e32 v123, v122, v120
	v_fma_f32 v124, -v119, v123, v122
	v_fmac_f32_e32 v123, v124, v120
	v_fma_f32 v119, -v119, v123, v122
	v_div_fmas_f32 v119, v119, v120, v123
	v_div_fixup_f32 v118, v119, v118, v121
	v_mul_f32_e32 v117, v117, v118
	v_mul_f32_e32 v118, 0xbfb8aa3b, v216
	v_exp_f32_e32 v118, v118
	s_nop 0
	v_add_f32_e32 v118, 1.0, v118
	v_div_scale_f32 v119, s[0:1], v118, v118, v216
	v_rcp_f32_e32 v120, v119
	s_nop 0
	v_fma_f32 v121, -v119, v120, 1.0
	v_fmac_f32_e32 v120, v121, v120
	v_div_scale_f32 v121, vcc, v216, v118, v216
	v_mul_f32_e32 v122, v121, v120
	v_fma_f32 v123, -v119, v122, v121
	v_fmac_f32_e32 v122, v123, v120
	v_fma_f32 v119, -v119, v122, v121
	v_div_fmas_f32 v119, v119, v120, v122
	v_div_fixup_f32 v216, v119, v118, v216
	v_mul_f32_e32 v216, v199, v216
	v_cvt_pk_bf16_f32 v118, v117, s0
	v_lshl_add_u64 v[116:117], s[26:27], 0, v[114:115]
	v_cvt_pk_bf16_f32 v216, v216, s0
	v_lshl_add_u64 v[114:115], s[38:39], 0, v[114:115]
	global_store_short v[114:115], v216, off
	global_store_short v[116:117], v118, off
	v_fma_f32 v137, v137, v140, v217
	v_fmac_f32_e32 v217, v135, v140
	v_fmac_f32_e32 v137, v135, v141
	v_fmac_f32_e32 v217, v138, v141
	v_fmac_f32_e32 v137, v138, v142
	v_fmac_f32_e32 v217, v139, v142
	v_fma_f32 v133, v136, v204, v205
	v_fmac_f32_e32 v205, v134, v204
	v_fmac_f32_e32 v133, v134, v206
	v_mul_f32_e32 v134, 0xbfb8aa3b, v137
	v_exp_f32_e32 v134, v134
	v_fmac_f32_e32 v205, v202, v206
	v_add_f32_e32 v134, 1.0, v134
	v_fmac_f32_e32 v133, v202, v207
	v_div_scale_f32 v135, s[0:1], v134, v134, v137
	v_rcp_f32_e32 v136, v135
	v_fmac_f32_e32 v205, v203, v207
	v_fma_f32 v138, -v135, v136, 1.0
	v_fmac_f32_e32 v136, v138, v136
	v_div_scale_f32 v138, vcc, v137, v134, v137
	v_mul_f32_e32 v139, v138, v136
	v_fma_f32 v140, -v135, v139, v138
	v_fmac_f32_e32 v139, v140, v136
	v_fma_f32 v135, -v135, v139, v138
	v_div_fmas_f32 v135, v135, v136, v139
	v_div_fixup_f32 v134, v135, v134, v137
	v_mul_f32_e32 v133, v133, v134
	v_mul_f32_e32 v134, 0xbfb8aa3b, v217
	v_exp_f32_e32 v134, v134
	s_nop 0
	v_add_f32_e32 v134, 1.0, v134
	v_div_scale_f32 v135, s[0:1], v134, v134, v217
	v_rcp_f32_e32 v136, v135
	s_nop 0
	v_fma_f32 v137, -v135, v136, 1.0
	v_fmac_f32_e32 v136, v137, v136
	v_div_scale_f32 v137, vcc, v217, v134, v217
	v_mul_f32_e32 v138, v137, v136
	v_fma_f32 v139, -v135, v138, v137
	v_fmac_f32_e32 v138, v139, v136
	v_fma_f32 v135, -v135, v138, v137
	v_div_fmas_f32 v135, v135, v136, v138
	v_div_fixup_f32 v217, v135, v134, v217
	v_mul_f32_e32 v217, v205, v217
	v_cvt_pk_bf16_f32 v134, v133, s0
	v_lshl_add_u64 v[132:133], s[26:27], 0, v[130:131]
	v_cvt_pk_bf16_f32 v217, v217, s0
	v_lshl_add_u64 v[130:131], s[38:39], 0, v[130:131]
	global_store_short v[130:131], v217, off
	global_store_short v[132:133], v134, off
	s_and_saveexec_b64 s[40:41], s[44:45]
	v_fma_f32 v153, v153, v156, v218
	v_fmac_f32_e32 v218, v151, v156
	v_fmac_f32_e32 v153, v151, v157
	v_fmac_f32_e32 v218, v154, v157
	v_fmac_f32_e32 v153, v154, v158
	v_fmac_f32_e32 v218, v155, v158
	v_fma_f32 v149, v152, v210, v211
	v_fmac_f32_e32 v211, v150, v210
	v_fmac_f32_e32 v149, v150, v212
	v_mul_f32_e32 v150, 0xbfb8aa3b, v153
	v_exp_f32_e32 v150, v150
	v_fmac_f32_e32 v211, v208, v212
	v_add_f32_e32 v150, 1.0, v150
	v_fmac_f32_e32 v149, v208, v213
	v_div_scale_f32 v151, s[0:1], v150, v150, v153
	v_rcp_f32_e32 v152, v151
	v_fmac_f32_e32 v211, v209, v213
	v_fma_f32 v154, -v151, v152, 1.0
	v_fmac_f32_e32 v152, v154, v152
	v_div_scale_f32 v154, vcc, v153, v150, v153
	v_mul_f32_e32 v155, v154, v152
	v_fma_f32 v156, -v151, v155, v154
	v_fmac_f32_e32 v155, v156, v152
	v_fma_f32 v151, -v151, v155, v154
	v_div_fmas_f32 v151, v151, v152, v155
	v_div_fixup_f32 v150, v151, v150, v153
	v_mul_f32_e32 v149, v149, v150
	v_mul_f32_e32 v150, 0xbfb8aa3b, v218
	v_exp_f32_e32 v150, v150
	s_nop 0
	v_add_f32_e32 v150, 1.0, v150
	v_div_scale_f32 v151, s[0:1], v150, v150, v218
	v_rcp_f32_e32 v152, v151
	s_nop 0
	v_fma_f32 v153, -v151, v152, 1.0
	v_fmac_f32_e32 v152, v153, v152
	v_div_scale_f32 v153, vcc, v218, v150, v218
	v_mul_f32_e32 v154, v153, v152
	v_fma_f32 v155, -v151, v154, v153
	v_fmac_f32_e32 v154, v155, v152
	v_fma_f32 v151, -v151, v154, v153
	v_div_fmas_f32 v151, v151, v152, v154
	v_div_fixup_f32 v218, v151, v150, v218
	v_mul_f32_e32 v218, v211, v218
	v_cvt_pk_bf16_f32 v150, v149, s0
	v_lshl_add_u64 v[148:149], s[26:27], 0, v[146:147]
	v_cvt_pk_bf16_f32 v218, v218, s0
	v_lshl_add_u64 v[146:147], s[38:39], 0, v[146:147]
	global_store_short v[146:147], v218, off
	global_store_short v[148:149], v150, off
	s_or_b64 exec, exec, s[40:41]
	s_branch .LBB0_1260
